# FINAL phase: the four gain vectors are loaded once before the row loop instead of once per row and quarter (four fewer serialized round trips per row)
# speedup vs baseline: 1.0015x; 1.0015x over previous
; DI int opaque_tid() { int t = threadIdx.x; asm volatile("" : "+v"(t)); return t; }
; DI void final_phase(KP p) {
;   const int tid = opaque_tid(), wid = tid >> 6, lane = tid & 63;
;   const float* P4 = (const float*)(p->ws + OFF_P4); const float* fg = p->in[3]; const bf16_t* XR = (const bf16_t*)(p->ws + OFF_XR);
;   for (int row = blockIdx.x * 8 + wid; row < T; row += gridDim.x * 8) {
;     const float rs = row_rstd(P4, 4, 1.f / 1024.f, row);
; #pragma unroll
;     for (int q = 0; q < 4; ++q) {
;       const u32x2 xw = *(const u32x2*)(XR + (size_t)row * DM + 256 * q + 4 * lane);
;       f32x4 v; v[0] = __uint_as_float(xw.x << 16); v[1] = __uint_as_float(xw.x & 0xffff0000u); v[2] = __uint_as_float(xw.y << 16); v[3] = __uint_as_float(xw.y & 0xffff0000u);
;       const f32x4 g = *(const f32x4*)(fg + 256 * q + 4 * lane);
;       *(f32x4*)(p->out + (size_t)row * DM + 256 * q + 4 * lane) = v * rs * g;
;     }
; __global__ void __launch_bounds__(512) mega(Params p_unused) {
;     ...
;     KP p = (KP)__builtin_amdgcn_kernarg_segment_ptr(); asm volatile("" : "+s"(p));
;     unsigned char* ws = p->ws;
;     bf16_t* XB = (bf16_t*)(ws + OFF_XR);
;     bf16_t* VTA = (bf16_t*)(ws + OFF_A);
;     float* P4 = (float*)(ws + OFF_P4); float* PQ = (float*)(ws + OFF_PQ); float* PKV = (float*)(ws + OFF_PKV);
;     const float* rope = (const float*)(ws + OFF_ROPE);
;     bf16_t* BIG = (bf16_t*)(ws + OFF_BIG);
;     bf16_t* WM = (bf16_t*)(ws + OFF_W + W_MIX);
;     const unsigned op = PROG[pc]; const int kind = op & 15, layer = (op >> 4) & 3, sub = (op >> 6) & 1, sync = (op >> 7) & 1;
;     if (kind == OP_END) break;
.LBB0_11:
	s_mov_b64 s[0:1], s[90:91]
	v_mov_b32_e32 v0, s21
	v_writelane_b32 v255, s0, 16
	s_load_dwordx2 s[80:81], s[0:1], 0xe8
	s_mov_b64 s[16:17], 0
	v_writelane_b32 v255, s1, 17
	v_writelane_b32 v255, s21, 18
	s_waitcnt lgkmcnt(0)
	s_add_u32 s0, s80, 0x17300000
	s_addc_u32 s1, s81, 0
	v_writelane_b32 v255, s0, 19
	s_nop 1
	v_writelane_b32 v255, s1, 20
	s_add_u32 s0, s80, 0x17000000
	s_addc_u32 s1, s81, 0
	v_writelane_b32 v255, s0, 21
	s_nop 1
	v_writelane_b32 v255, s1, 22
	s_add_u32 s0, s80, 0x170c0000
	s_addc_u32 s1, s81, 0
	s_add_u32 s10, s80, 0x170e0000
	s_addc_u32 s11, s81, 0
	s_add_u32 s54, s80, 0x4000000
	v_writelane_b32 v255, s0, 23
	s_addc_u32 s55, s81, 0
	s_nop 0
	v_writelane_b32 v255, s1, 24
	s_add_u32 s0, s80, 0x16100000
	s_addc_u32 s1, s81, 0
	v_writelane_b32 v255, s0, 25
	s_nop 1
	v_writelane_b32 v255, s1, 26
	s_getpc_b64 s[0:1]
	s_add_u32 s0, s0, _ZL4PROG@rel32@lo+4
	s_addc_u32 s1, s1, _ZL4PROG@rel32@hi+12
	global_load_ubyte v0, v0, s[0:1]
	s_waitcnt vmcnt(0)
	v_readfirstlane_b32 s0, v0
	s_and_b32 s64, s0, 15
	s_nop 0
	v_writelane_b32 v255, s0, 27
	s_bfe_u32 s0, s0, 0x20004
	v_writelane_b32 v255, s0, 28
	s_mov_b64 s[0:1], -1
	v_writelane_b32 v255, s0, 29
	s_cmp_lt_i32 s64, 6
	s_nop 0
	v_writelane_b32 v255, s1, 30
	s_cbranch_scc1 .LBB0_23
	s_mov_b64 s[12:13], -1
	s_mov_b64 s[30:31], 0
	s_cmp_gt_i32 s64, 9
	s_mov_b64 s[42:43], 0
	s_mov_b64 s[4:5], 0
	s_cbranch_scc0 .LBB0_201
	s_cmp_gt_i32 s64, 10
	s_cbranch_scc0 .LBB0_97
	s_cmp_gt_i32 s64, 11
	s_cbranch_scc0 .LBB0_20
	s_mov_b64 s[4:5], -1
	s_mov_b64 s[12:13], 0
	s_cmp_eq_u32 s64, 12
	s_cbranch_scc0 .LBB0_20
	v_mov_b32_e32 v0, v194
	v_readlane_b32 s0, v254, 4
	v_ashrrev_i32_e32 v2, 6, v0
	s_nop 0
	v_add_u32_e32 v2, s0, v2
	s_mov_b32 s0, 0x8000
	v_cmp_gt_i32_e32 vcc, s0, v2
	s_and_saveexec_b64 s[4:5], vcc
	v_readlane_b32 s16, v255, 21
	v_readlane_b32 s17, v255, 22
	s_cbranch_execz .LBB0_19
	v_readlane_b32 s8, v255, 16
	v_readlane_b32 s9, v255, 17
	s_load_dwordx2 s[0:1], s[8:9], 0x18
	v_lshlrev_b32_e32 v0, 2, v0
	v_and_b32_e32 v3, 0xfc, v0
	v_readlane_b32 s14, v255, 19
	v_lshlrev_b32_e32 v0, 1, v3
	v_readlane_b32 s15, v255, 20
	s_nop 1
	v_lshl_add_u64 v[4:5], s[14:15], 0, v[0:1]
	v_lshlrev_b32_e32 v0, 2, v3
	s_waitcnt lgkmcnt(0)
	v_lshl_add_u64 v[6:7], s[0:1], 0, v[0:1]
	s_load_dwordx2 s[0:1], s[8:9], 0xe0
	s_mov_b64 s[14:15], 0
	s_waitcnt lgkmcnt(0)
	v_lshl_add_u64 v[8:9], s[0:1], 0, v[0:1]
	global_load_dwordx4 v[222:225], v[6:7], off
	global_load_dwordx4 v[226:229], v[6:7], off offset:1024
	global_load_dwordx4 v[230:233], v[6:7], off offset:2048
	global_load_dwordx4 v[234:237], v[6:7], off offset:3072
.LBB0_18:
	v_ashrrev_i32_e32 v3, 31, v2
	v_lshl_add_u64 v[10:11], v[2:3], 2, s[16:17]
	v_add_co_u32_e32 v14, vcc, 0x20000, v10
	global_load_dword v12, v[10:11], off
	s_nop 0
	v_addc_co_u32_e32 v15, vcc, 0, v11, vcc
	v_add_co_u32_e32 v16, vcc, 0x40000, v10
	global_load_dword v14, v[14:15], off
	s_nop 0
	v_addc_co_u32_e32 v17, vcc, 0, v11, vcc
	v_add_co_u32_e32 v10, vcc, 0x60000, v10
	global_load_dword v13, v[16:17], off
	s_nop 0
	v_addc_co_u32_e32 v11, vcc, 0, v11, vcc
	global_load_dword v15, v[10:11], off
	s_waitcnt vmcnt(0)
	v_pk_add_f32 v[10:11], v[12:13], v[14:15]
	s_nop 0
	v_add_f32_e32 v0, v10, v11
	v_fmamk_f32 v0, v0, 0x3a800000, v195
	v_cmp_gt_f32_e32 vcc, s57, v0
	v_mul_f32_e32 v10, 0x4b800000, v0
	s_nop 0
	v_cndmask_b32_e32 v0, v0, v10, vcc
	v_rsq_f32_e32 v0, v0
	s_nop 0
	v_mul_f32_e32 v10, 0x45800000, v0
	v_cndmask_b32_e32 v0, v0, v10, vcc
	v_lshlrev_b64 v[10:11], 11, v[2:3]
	v_lshl_add_u64 v[14:15], v[4:5], 0, v[10:11]
	v_lshlrev_b64 v[10:11], 12, v[2:3]
	v_lshl_add_u64 v[16:17], v[8:9], 0, v[10:11]
	global_load_dwordx2 v[10:11], v[14:15], off
	v_add_u32_e32 v2, s96, v2
	v_cmp_lt_i32_e32 vcc, s89, v2
	s_or_b64 s[14:15], vcc, s[14:15]
	s_waitcnt vmcnt(0)
	v_lshlrev_b32_e32 v18, 16, v10
	v_and_b32_e32 v19, 0xffff0000, v10
	v_lshlrev_b32_e32 v20, 16, v11
	v_and_b32_e32 v21, 0xffff0000, v11
	v_pk_mul_f32 v[18:19], v[0:1], v[18:19] op_sel_hi:[0,1]
	v_pk_mul_f32 v[20:21], v[0:1], v[20:21] op_sel_hi:[0,1]
	s_waitcnt vmcnt(0)
	v_pk_mul_f32 v[12:13], v[224:225], v[20:21]
	v_pk_mul_f32 v[10:11], v[222:223], v[18:19]
	global_store_dwordx4 v[16:17], v[10:13], off
	global_load_dwordx2 v[10:11], v[14:15], off offset:512
	s_waitcnt vmcnt(0)
	v_lshlrev_b32_e32 v18, 16, v10
	v_and_b32_e32 v19, 0xffff0000, v10
	v_lshlrev_b32_e32 v20, 16, v11
	v_and_b32_e32 v21, 0xffff0000, v11
	v_pk_mul_f32 v[18:19], v[0:1], v[18:19] op_sel_hi:[0,1]
	v_pk_mul_f32 v[20:21], v[0:1], v[20:21] op_sel_hi:[0,1]
	s_waitcnt vmcnt(0)
	v_pk_mul_f32 v[12:13], v[228:229], v[20:21]
	v_pk_mul_f32 v[10:11], v[226:227], v[18:19]
	global_store_dwordx4 v[16:17], v[10:13], off offset:1024
	global_load_dwordx2 v[10:11], v[14:15], off offset:1024
	s_waitcnt vmcnt(0)
	v_lshlrev_b32_e32 v18, 16, v10
	v_and_b32_e32 v19, 0xffff0000, v10
	v_lshlrev_b32_e32 v20, 16, v11
	v_and_b32_e32 v21, 0xffff0000, v11
	v_pk_mul_f32 v[18:19], v[0:1], v[18:19] op_sel_hi:[0,1]
	v_pk_mul_f32 v[20:21], v[0:1], v[20:21] op_sel_hi:[0,1]
	s_waitcnt vmcnt(0)
	v_pk_mul_f32 v[12:13], v[232:233], v[20:21]
	v_pk_mul_f32 v[10:11], v[230:231], v[18:19]
	global_store_dwordx4 v[16:17], v[10:13], off offset:2048
	global_load_dwordx2 v[10:11], v[14:15], off offset:1536
	s_waitcnt vmcnt(0)
	v_lshlrev_b32_e32 v14, 16, v10
	v_and_b32_e32 v15, 0xffff0000, v10
	v_lshlrev_b32_e32 v18, 16, v11
	v_and_b32_e32 v19, 0xffff0000, v11
	v_pk_mul_f32 v[14:15], v[0:1], v[14:15] op_sel_hi:[0,1]
	v_pk_mul_f32 v[18:19], v[0:1], v[18:19] op_sel_hi:[0,1]
	s_waitcnt vmcnt(0)
	v_pk_mul_f32 v[12:13], v[236:237], v[18:19]
	v_pk_mul_f32 v[10:11], v[234:235], v[14:15]
	global_store_dwordx4 v[16:17], v[10:13], off offset:3072
	s_andn2_b64 exec, exec, s[14:15]
	s_cbranch_execnz .LBB0_18
